# grid barriers 2..15: every workgroup polls the cross-XCD arrival counter directly (no second and third release word hop)
# speedup vs baseline: 1.0055x; 1.0055x over previous
.LBB0_381:
	s_or_b64 exec, exec, s[10:11]
	s_waitcnt lgkmcnt(1)
	v_cvt_f32_u32_e32 v5, v3
	s_waitcnt vmcnt(0)
	v_readfirstlane_b32 s8, v4
	v_sub_u32_e32 v4, 0, v3
	v_rcp_iflag_f32_e32 v5, v5
	v_add_u32_e32 v6, s8, v1
	v_mul_f32_e32 v5, 0x4f7ffffe, v5
	v_cvt_u32_f32_e32 v5, v5
	v_mul_lo_u32 v1, v4, v5
	v_mul_hi_u32 v1, v5, v1
	v_add_u32_e32 v1, v5, v1
	v_mul_hi_u32 v1, v6, v1
	v_mul_lo_u32 v4, v1, v3
	v_sub_u32_e32 v4, v6, v4
	v_add_u32_e32 v5, 1, v1
	v_sub_u32_e32 v7, v4, v3
	v_cmp_ge_u32_e32 vcc, v4, v3
	s_nop 1
	v_cndmask_b32_e32 v1, v1, v5, vcc
	v_cndmask_b32_e32 v4, v4, v7, vcc
	v_add_u32_e32 v5, 1, v1
	v_cmp_ge_u32_e32 vcc, v4, v3
	v_add_u32_e32 v4, 1, v6
	s_nop 0
	v_cndmask_b32_e32 v1, v1, v5, vcc
	v_mul_lo_u32 v5, v3, v1
	v_add_u32_e32 v3, v5, v3
	v_cmp_ne_u32_e32 vcc, v4, v3
	s_and_saveexec_b64 s[8:9], vcc
	s_xor_b64 s[8:9], exec, s[8:9]
	s_cbranch_execz .LBB0_395
	s_add_i32 s94, s24, 0x900
	s_lshl_b64 s[10:11], s[94:95], 2
	s_add_u32 s12, s92, s10
	s_addc_u32 s13, s93, s11
	s_waitcnt lgkmcnt(0)
	v_add_u32_e32 v7, 1, v1
	v_mul_lo_u32 v7, v7, v0
	buffer_inv sc1
	global_load_dword v0, v2, s[40:41] offset:-256 sc1
	s_waitcnt vmcnt(0)
	v_cmp_lt_u32_e32 vcc, v0, v7
	s_and_saveexec_b64 s[10:11], vcc
	s_cbranch_execz .LBB0_394
	s_mov_b32 s25, 1
	s_mov_b64 s[14:15], 0
	s_branch .LBB0_385

.LBB0_387:
	global_load_dword v0, v2, s[40:41] offset:-256 sc1
	s_add_i32 s25, s25, 1
	s_mov_b64 s[20:21], -1
	s_waitcnt vmcnt(0)
	v_cmp_ge_u32_e32 vcc, v0, v7
	s_orn2_b64 s[18:19], vcc, exec
	s_branch .LBB0_384

.LBB0_398:
	s_or_b64 exec, exec, s[12:13]
	v_cvt_f32_u32_e32 v4, v0
	s_waitcnt vmcnt(0)
	v_readfirstlane_b32 s10, v3
	v_sub_u32_e32 v3, 0, v0
	s_mov_b64 s[12:13], -1
	v_rcp_iflag_f32_e32 v4, v4
	v_add_u32_e32 v1, s10, v1
	v_add_u32_e32 v5, 1, v1
	v_mul_f32_e32 v4, 0x4f7ffffe, v4
	v_cvt_u32_f32_e32 v4, v4
	v_mul_lo_u32 v3, v3, v4
	v_mul_hi_u32 v3, v4, v3
	v_add_u32_e32 v3, v4, v3
	v_mul_hi_u32 v3, v1, v3
	v_mul_lo_u32 v4, v3, v0
	v_sub_u32_e32 v1, v1, v4
	v_add_u32_e32 v6, 1, v3
	v_sub_u32_e32 v4, v1, v0
	v_cmp_ge_u32_e32 vcc, v1, v0
	s_nop 1
	v_cndmask_b32_e32 v3, v3, v6, vcc
	v_cndmask_b32_e32 v1, v1, v4, vcc
	v_add_u32_e32 v4, 1, v3
	v_cmp_ge_u32_e32 vcc, v1, v0
	s_nop 1
	v_cndmask_b32_e32 v3, v3, v4, vcc
	v_mul_lo_u32 v1, v0, v3
	v_add_u32_e32 v0, v1, v0
	v_cmp_ne_u32_e32 vcc, v5, v0
	v_mov_b32_e32 v7, v0
	v_mov_b64_e32 v[0:1], s[40:41]
	s_and_saveexec_b64 s[10:11], vcc
	s_cbranch_execz .LBB0_410
	global_load_dword v0, v2, s[40:41] offset:-256 sc1
	s_mov_b64 s[14:15], 0
	s_waitcnt vmcnt(0)
	v_cmp_lt_u32_e32 vcc, v0, v7
	s_and_saveexec_b64 s[12:13], vcc
	s_cbranch_execz .LBB0_409
	s_mov_b32 s25, 1
	s_branch .LBB0_402

.LBB0_436:
	s_or_b64 exec, exec, s[10:11]
	s_waitcnt lgkmcnt(1)
	v_cvt_f32_u32_e32 v5, v3
	s_waitcnt vmcnt(0)
	v_readfirstlane_b32 s8, v4
	v_sub_u32_e32 v4, 0, v3
	v_rcp_iflag_f32_e32 v5, v5
	v_add_u32_e32 v6, s8, v1
	v_mul_f32_e32 v5, 0x4f7ffffe, v5
	v_cvt_u32_f32_e32 v5, v5
	v_mul_lo_u32 v1, v4, v5
	v_mul_hi_u32 v1, v5, v1
	v_add_u32_e32 v1, v5, v1
	v_mul_hi_u32 v1, v6, v1
	v_mul_lo_u32 v4, v1, v3
	v_sub_u32_e32 v4, v6, v4
	v_add_u32_e32 v5, 1, v1
	v_cmp_ge_u32_e32 vcc, v4, v3
	s_nop 1
	v_cndmask_b32_e32 v1, v1, v5, vcc
	v_sub_u32_e32 v5, v4, v3
	v_cndmask_b32_e32 v4, v4, v5, vcc
	v_add_u32_e32 v5, 1, v1
	v_cmp_ge_u32_e32 vcc, v4, v3
	v_add_u32_e32 v4, 1, v6
	s_nop 0
	v_cndmask_b32_e32 v1, v1, v5, vcc
	v_mul_lo_u32 v5, v3, v1
	v_add_u32_e32 v3, v5, v3
	v_cmp_ne_u32_e32 vcc, v4, v3
	s_and_saveexec_b64 s[8:9], vcc
	s_xor_b64 s[8:9], exec, s[8:9]
	s_cbranch_execz .LBB0_450
	s_add_i32 s94, s24, 0x900
	s_lshl_b64 s[10:11], s[94:95], 2
	s_add_u32 s12, s92, s10
	s_addc_u32 s13, s93, s11
	s_waitcnt lgkmcnt(0)
	v_add_u32_e32 v7, 1, v1
	v_mul_lo_u32 v7, v7, v0
	buffer_inv sc1
	global_load_dword v0, v2, s[40:41] offset:-256 sc1
	s_waitcnt vmcnt(0)
	v_cmp_lt_u32_e32 vcc, v0, v7
	s_and_saveexec_b64 s[10:11], vcc
	s_cbranch_execz .LBB0_449
	s_mov_b32 s25, 1
	s_mov_b64 s[14:15], 0
	s_branch .LBB0_440

.LBB0_453:
	s_or_b64 exec, exec, s[12:13]
	s_waitcnt vmcnt(0)
	v_readfirstlane_b32 s10, v3
	v_cvt_f32_u32_e32 v3, v0
	v_sub_u32_e32 v4, 0, v0
	v_add_u32_e32 v1, s10, v1
	s_mov_b64 s[12:13], -1
	v_rcp_iflag_f32_e32 v3, v3
	s_nop 0
	v_mul_f32_e32 v3, 0x4f7ffffe, v3
	v_cvt_u32_f32_e32 v3, v3
	v_mul_lo_u32 v4, v4, v3
	v_mul_hi_u32 v4, v3, v4
	v_add_u32_e32 v3, v3, v4
	v_mul_hi_u32 v3, v1, v3
	v_mul_lo_u32 v4, v3, v0
	v_sub_u32_e32 v4, v1, v4
	v_cmp_ge_u32_e32 vcc, v4, v0
	v_add_u32_e32 v5, 1, v3
	v_add_u32_e32 v1, 1, v1
	v_cndmask_b32_e32 v3, v3, v5, vcc
	v_sub_u32_e32 v5, v4, v0
	v_cndmask_b32_e32 v4, v4, v5, vcc
	v_cmp_ge_u32_e32 vcc, v4, v0
	v_add_u32_e32 v4, 1, v3
	s_nop 0
	v_cndmask_b32_e32 v3, v3, v4, vcc
	v_mul_lo_u32 v4, v0, v3
	v_add_u32_e32 v0, v4, v0
	v_cmp_ne_u32_e32 vcc, v1, v0
	v_mov_b32_e32 v7, v0
	v_mov_b64_e32 v[0:1], s[40:41]
	s_and_saveexec_b64 s[10:11], vcc
	s_cbranch_execz .LBB0_465
	global_load_dword v0, v2, s[40:41] offset:-256 sc1
	s_mov_b64 s[14:15], 0
	s_waitcnt vmcnt(0)
	v_cmp_lt_u32_e32 vcc, v0, v7
	s_and_saveexec_b64 s[12:13], vcc
	s_cbranch_execz .LBB0_464
	s_mov_b32 s25, 1
	s_branch .LBB0_457

.LBB0_631:
	s_or_b64 exec, exec, s[12:13]
	s_waitcnt lgkmcnt(1)
	v_cvt_f32_u32_e32 v5, v3
	s_waitcnt vmcnt(0)
	v_readfirstlane_b32 s7, v4
	v_sub_u32_e32 v4, 0, v3
	v_rcp_iflag_f32_e32 v5, v5
	v_add_u32_e32 v6, s7, v1
	v_mul_f32_e32 v5, 0x4f7ffffe, v5
	v_cvt_u32_f32_e32 v5, v5
	v_mul_lo_u32 v1, v4, v5
	v_mul_hi_u32 v1, v5, v1
	v_add_u32_e32 v1, v5, v1
	v_mul_hi_u32 v1, v6, v1
	v_mul_lo_u32 v4, v1, v3
	v_sub_u32_e32 v4, v6, v4
	v_add_u32_e32 v5, 1, v1
	v_cmp_ge_u32_e32 vcc, v4, v3
	s_nop 1
	v_cndmask_b32_e32 v1, v1, v5, vcc
	v_sub_u32_e32 v5, v4, v3
	v_cndmask_b32_e32 v4, v4, v5, vcc
	v_add_u32_e32 v5, 1, v1
	v_cmp_ge_u32_e32 vcc, v4, v3
	v_add_u32_e32 v4, 1, v6
	s_nop 0
	v_cndmask_b32_e32 v1, v1, v5, vcc
	v_mul_lo_u32 v5, v3, v1
	v_add_u32_e32 v3, v5, v3
	v_cmp_ne_u32_e32 vcc, v4, v3
	s_and_saveexec_b64 s[10:11], vcc
	s_xor_b64 s[10:11], exec, s[10:11]
	s_cbranch_execz .LBB0_645
	s_add_i32 s94, s6, 0x900
	s_lshl_b64 s[12:13], s[94:95], 2
	s_add_u32 s14, s92, s12
	s_addc_u32 s15, s93, s13
	s_waitcnt lgkmcnt(0)
	v_add_u32_e32 v7, 1, v1
	v_mul_lo_u32 v7, v7, v0
	buffer_inv sc1
	global_load_dword v0, v2, s[40:41] offset:-256 sc1
	s_waitcnt vmcnt(0)
	v_cmp_lt_u32_e32 vcc, v0, v7
	s_and_saveexec_b64 s[12:13], vcc
	s_cbranch_execz .LBB0_644
	s_mov_b32 s7, 1
	s_mov_b64 s[16:17], 0
	s_branch .LBB0_635

.LBB0_637:
	global_load_dword v0, v2, s[40:41] offset:-256 sc1
	s_add_i32 s7, s7, 1
	s_mov_b64 s[22:23], -1
	s_waitcnt vmcnt(0)
	v_cmp_ge_u32_e32 vcc, v0, v7
	s_orn2_b64 s[20:21], vcc, exec
	s_branch .LBB0_634

.LBB0_648:
	s_or_b64 exec, exec, s[12:13]
	s_waitcnt vmcnt(0)
	v_readfirstlane_b32 s7, v3
	v_cvt_f32_u32_e32 v3, v0
	v_sub_u32_e32 v4, 0, v0
	v_add_u32_e32 v1, s7, v1
	s_mov_b64 s[12:13], -1
	v_rcp_iflag_f32_e32 v3, v3
	s_nop 0
	v_mul_f32_e32 v3, 0x4f7ffffe, v3
	v_cvt_u32_f32_e32 v3, v3
	v_mul_lo_u32 v4, v4, v3
	v_mul_hi_u32 v4, v3, v4
	v_add_u32_e32 v3, v3, v4
	v_mul_hi_u32 v3, v1, v3
	v_mul_lo_u32 v4, v3, v0
	v_sub_u32_e32 v4, v1, v4
	v_cmp_ge_u32_e32 vcc, v4, v0
	v_add_u32_e32 v5, 1, v3
	v_add_u32_e32 v1, 1, v1
	v_cndmask_b32_e32 v3, v3, v5, vcc
	v_sub_u32_e32 v5, v4, v0
	v_cndmask_b32_e32 v4, v4, v5, vcc
	v_cmp_ge_u32_e32 vcc, v4, v0
	v_add_u32_e32 v4, 1, v3
	s_nop 0
	v_cndmask_b32_e32 v3, v3, v4, vcc
	v_mul_lo_u32 v4, v0, v3
	v_add_u32_e32 v0, v4, v0
	v_cmp_ne_u32_e32 vcc, v1, v0
	v_mov_b32_e32 v7, v0
	v_mov_b64_e32 v[0:1], s[40:41]
	s_and_saveexec_b64 s[10:11], vcc
	s_cbranch_execz .LBB0_660
	global_load_dword v0, v2, s[40:41] offset:-256 sc1
	s_mov_b64 s[14:15], 0
	s_waitcnt vmcnt(0)
	v_cmp_lt_u32_e32 vcc, v0, v7
	s_and_saveexec_b64 s[12:13], vcc
	s_cbranch_execz .LBB0_659
	s_mov_b32 s7, 1
	s_branch .LBB0_652

.LBB0_654:
	global_load_dword v0, v2, s[40:41] offset:-256 sc1
	s_add_i32 s7, s7, 1
	s_mov_b64 s[20:21], -1
	s_waitcnt vmcnt(0)
	v_cmp_ge_u32_e32 vcc, v0, v7
	s_orn2_b64 s[18:19], vcc, exec
	s_branch .LBB0_651

.LBB0_776:
	s_or_b64 exec, exec, s[14:15]
	s_waitcnt vmcnt(0)
	v_readfirstlane_b32 s7, v3
	v_cvt_f32_u32_e32 v3, v0
	v_sub_u32_e32 v4, 0, v0
	v_add_u32_e32 v1, s7, v1
	s_mov_b64 s[14:15], -1
	v_rcp_iflag_f32_e32 v3, v3
	s_nop 0
	v_mul_f32_e32 v3, 0x4f7ffffe, v3
	v_cvt_u32_f32_e32 v3, v3
	v_mul_lo_u32 v4, v4, v3
	v_mul_hi_u32 v4, v3, v4
	v_add_u32_e32 v3, v3, v4
	v_mul_hi_u32 v3, v1, v3
	v_mul_lo_u32 v4, v3, v0
	v_sub_u32_e32 v4, v1, v4
	v_cmp_ge_u32_e32 vcc, v4, v0
	v_add_u32_e32 v5, 1, v3
	v_add_u32_e32 v1, 1, v1
	v_cndmask_b32_e32 v3, v3, v5, vcc
	v_sub_u32_e32 v5, v4, v0
	v_cndmask_b32_e32 v4, v4, v5, vcc
	v_cmp_ge_u32_e32 vcc, v4, v0
	v_add_u32_e32 v4, 1, v3
	s_nop 0
	v_cndmask_b32_e32 v3, v3, v4, vcc
	v_mul_lo_u32 v4, v0, v3
	v_add_u32_e32 v0, v4, v0
	v_cmp_ne_u32_e32 vcc, v1, v0
	v_mov_b32_e32 v7, v0
	v_mov_b64_e32 v[0:1], s[40:41]
	s_and_saveexec_b64 s[12:13], vcc
	s_cbranch_execz .LBB0_788
	global_load_dword v0, v2, s[40:41] offset:-256 sc1
	s_mov_b64 s[16:17], 0
	s_waitcnt vmcnt(0)
	v_cmp_lt_u32_e32 vcc, v0, v7
	s_and_saveexec_b64 s[14:15], vcc
	s_cbranch_execz .LBB0_787
	s_mov_b32 s7, 1
	s_branch .LBB0_780

.LBB0_893:
	s_or_b64 exec, exec, s[10:11]
	s_waitcnt vmcnt(0)
	v_readfirstlane_b32 s8, v3
	v_cvt_f32_u32_e32 v3, v0
	v_sub_u32_e32 v4, 0, v0
	v_add_u32_e32 v1, s8, v1
	s_mov_b64 s[10:11], -1
	v_rcp_iflag_f32_e32 v3, v3
	s_nop 0
	v_mul_f32_e32 v3, 0x4f7ffffe, v3
	v_cvt_u32_f32_e32 v3, v3
	v_mul_lo_u32 v4, v4, v3
	v_mul_hi_u32 v4, v3, v4
	v_add_u32_e32 v3, v3, v4
	v_mul_hi_u32 v3, v1, v3
	v_mul_lo_u32 v4, v3, v0
	v_sub_u32_e32 v4, v1, v4
	v_cmp_ge_u32_e32 vcc, v4, v0
	v_add_u32_e32 v5, 1, v3
	v_add_u32_e32 v1, 1, v1
	v_cndmask_b32_e32 v3, v3, v5, vcc
	v_sub_u32_e32 v5, v4, v0
	v_cndmask_b32_e32 v4, v4, v5, vcc
	v_cmp_ge_u32_e32 vcc, v4, v0
	v_add_u32_e32 v4, 1, v3
	s_nop 0
	v_cndmask_b32_e32 v3, v3, v4, vcc
	v_mul_lo_u32 v4, v0, v3
	v_add_u32_e32 v0, v4, v0
	v_cmp_ne_u32_e32 vcc, v1, v0
	v_mov_b32_e32 v7, v0
	v_mov_b64_e32 v[0:1], s[40:41]
	s_and_saveexec_b64 s[8:9], vcc
	s_cbranch_execz .LBB0_905
	global_load_dword v0, v2, s[40:41] offset:-256 sc1
	s_mov_b64 s[12:13], 0
	s_waitcnt vmcnt(0)
	v_cmp_lt_u32_e32 vcc, v0, v7
	s_and_saveexec_b64 s[10:11], vcc
	s_cbranch_execz .LBB0_904
	s_mov_b32 s22, 1
	s_branch .LBB0_897

.LBB0_899:
	global_load_dword v0, v2, s[40:41] offset:-256 sc1
	s_add_i32 s22, s22, 1
	s_mov_b64 s[18:19], -1
	s_waitcnt vmcnt(0)
	v_cmp_ge_u32_e32 vcc, v0, v7
	s_orn2_b64 s[16:17], vcc, exec
	s_branch .LBB0_896
